# P6->P7: 496 proj GEMM units (pm>=128) run before the grid barrier on CUs 8..255 in the shadow of the P6 tail; rest after
# baseline (speedup 1.0000x reference)
.LBB0_1342:
	s_cmpk_lg_i32 s93, 0x100
	s_cbranch_scc1 .Lp7_xbar
	s_cmp_lt_u32 s62, 8
	s_cbranch_scc1 .Lp7_xbar
	s_movk_i32 s100, 0xf8
	s_movk_i32 s101, 0x1f0
	s_branch .Lp7_proj

.LBB0_1387:
	s_or_b64 exec, exec, s[36:37]
	s_waitcnt lgkmcnt(0)
	s_barrier
	s_mov_b32 s100, s93
	s_movk_i32 s101, 0x408
	s_cmpk_lg_i32 s93, 0x100
	s_cbranch_scc1 .Lp7_proj
	s_movk_i32 s100, 0xf8
	s_movk_i32 s101, 0x218
.Lp7_proj:
	s_mov_b32 s39, s62
	s_cmpk_eq_i32 s101, 0x408
	s_cbranch_scc1 .Lp7_jv
	s_sub_i32 s39, s62, 8
	s_cmp_lt_u32 s62, 8
	s_cselect_b32 s39, s101, s39
.Lp7_jv:
	s_cmpk_eq_i32 s101, 0x1f0
	s_cselect_b32 s18, 0x200, 0
	s_add_i32 s18, s18, s39
	s_cmpk_eq_i32 s101, 0x218
	s_cselect_b32 s0, 0x1f0, 0
	s_cmpk_ge_i32 s39, 0x200
	s_cselect_b32 s0, s0, 0
	s_add_i32 s18, s18, s0
	v_mov_b32_e32 v2, v228
	s_cmp_lt_i32 s39, s101
	s_cselect_b64 s[4:5], -1, 0
	s_cmp_ge_i32 s39, s101
	v_readfirstlane_b32 s6, v2
	s_cbranch_scc1 .LBB0_1401
	v_bfe_i32 v4, v2, 27, 1
	v_lshlrev_b32_e32 v3, 4, v2
	v_lshrrev_b32_e32 v4, 22, v4
	v_add_u32_e32 v4, v3, v4
	v_and_b32_e32 v4, 0xfffffc00, v4
	v_sub_u32_e32 v4, v3, v4
	v_ashrrev_i32_e32 v0, 31, v2
	v_lshrrev_b32_e32 v5, 4, v4
	v_lshrrev_b32_e32 v0, 26, v0
	v_bitop3_b32 v5, v5, v4, 32 bitop3:0x6c
	v_ashrrev_i32_e32 v4, 31, v4
	v_add_u32_e32 v0, v2, v0
	v_lshrrev_b32_e32 v4, 26, v4
	v_ashrrev_i32_e32 v0, 6, v0
	v_add_u32_e32 v4, v5, v4
	v_lshlrev_b32_e32 v6, 3, v0
	v_ashrrev_i32_e32 v4, 6, v4
	v_and_b32_e32 v6, -16, v6
	v_mul_i32_i24_e32 v7, 64, v4
	v_add_u32_e32 v6, v4, v6
	v_sub_u32_e32 v5, v5, v7
	v_mov_b32_e32 v9, 1
	v_lshlrev_b32_e32 v0, 5, v0
	v_ashrrev_i16_sdwa v5, v9, sext(v5) dst_sel:DWORD dst_unused:UNUSED_PAD src0_sel:DWORD src1_sel:BYTE_0
	v_lshlrev_b32_e32 v7, 1, v6
	v_lshrrev_b32_e32 v8, 2, v6
	v_and_b32_e32 v4, 3, v4
	s_mov_b32 s0, 0x7fffe0
	v_and_b32_e32 v0, 32, v0
	v_bfe_i32 v5, v5, 0, 16
	v_and_b32_e32 v7, 24, v7
	v_and_b32_e32 v8, 4, v8
	v_and_or_b32 v4, v6, s0, v4
	v_or3_b32 v4, v4, v8, v7
	v_add_lshl_u32 v5, v0, v5, 1
	v_add_u32_e32 v3, 0x2000, v3
	v_lshl_add_u32 v130, v4, 9, v5
	v_ashrrev_i32_e32 v4, 31, v3
	v_lshrrev_b32_e32 v4, 22, v4
	v_add_u32_e32 v4, v3, v4
	v_ashrrev_i32_e32 v4, 10, v4
	v_lshl_add_u32 v0, v6, 9, v5
	v_mul_i32_i24_e32 v5, 0x400, v4
	v_sub_u32_e32 v3, v3, v5
	v_lshrrev_b32_e32 v5, 4, v3
	v_bitop3_b32 v3, v5, v3, 32 bitop3:0x6c
	v_ashrrev_i32_e32 v6, 31, v3
	v_lshrrev_b32_e32 v6, 26, v6
	v_lshlrev_b32_e32 v5, 3, v4
	v_add_u32_e32 v6, v3, v6
	v_and_b32_e32 v5, -16, v5
	v_ashrrev_i32_e32 v7, 6, v6
	v_add_u32_e32 v5, v7, v5
	v_and_b32_e32 v7, 3, v7
	v_and_or_b32 v7, v5, s0, v7
	s_ashr_i32 s0, s18, 31
	s_lshr_b32 s0, s0, 30
	s_add_i32 s0, s18, s0
	s_ashr_i32 s8, s6, 6
	s_ashr_i32 s20, s0, 2
	s_and_b32 s0, s0, -4
	s_ashr_i32 s7, s6, 8
	s_lshl_b32 s28, s8, 10
	s_sub_i32 s18, s18, s0
	s_add_u32 s29, s76, 0x32aba000
	s_addc_u32 s30, s77, 0
	s_ashr_i32 s21, s20, 31
	s_lshl_b64 s[0:1], s[20:21], 17
	s_add_u32 s24, s29, s0
	s_addc_u32 s25, s30, s1
	v_readlane_b32 s0, v255, 44
	s_add_u32 s0, s76, s0
	s_addc_u32 s1, s77, 0
	s_add_u32 s21, s0, 0x11c0000
	s_addc_u32 s31, s1, 0
	s_ashr_i32 s19, s18, 31
	v_and_b32_e32 v6, 0xc0, v6
	s_lshl_b64 s[0:1], s[18:19], 17
	v_sub_u32_e32 v3, v3, v6
	s_add_u32 s26, s21, s0
	v_lshlrev_b32_e32 v4, 5, v4
	v_ashrrev_i16_sdwa v3, v9, sext(v3) dst_sel:DWORD dst_unused:UNUSED_PAD src0_sel:DWORD src1_sel:BYTE_0
	v_lshlrev_b32_e32 v6, 1, v5
	v_lshrrev_b32_e32 v8, 2, v5
	s_addc_u32 s27, s31, s1
	s_add_i32 s19, s28, 0
	v_and_b32_e32 v4, 32, v4
	v_bfe_i32 v3, v3, 0, 16
	v_and_b32_e32 v6, 24, v6
	v_and_b32_e32 v8, 4, v8
	s_add_i32 m0, s19, 0x10000
	v_or3_b32 v6, v7, v8, v6
	v_add_lshl_u32 v3, v4, v3, 1
	global_load_lds_dwordx4 v130, s[26:27]
	s_add_i32 m0, s19, 0x12000
	v_lshl_add_u32 v134, v6, 9, v3
	s_add_u32 s0, s26, 0x10000
	global_load_lds_dwordx4 v134, s[26:27]
	s_addc_u32 s1, s27, 0
	s_add_i32 m0, s19, 0x14000
	s_add_i32 s34, s19, 0x2000
	global_load_lds_dwordx4 v130, s[0:1]
	s_add_i32 m0, s19, 0x16000
	v_lshl_add_u32 v132, v5, 9, v3
	global_load_lds_dwordx4 v134, s[0:1]
	s_mov_b32 m0, s19
	s_add_u32 s0, s24, 0x10000
	global_load_lds_dwordx4 v0, s[24:25]
	s_mov_b32 m0, s34
	s_addc_u32 s1, s25, 0
	s_add_i32 s35, s19, 0x4000
	global_load_lds_dwordx4 v132, s[24:25]
	s_mov_b32 m0, s35
	s_add_i32 s36, s19, 0x6000
	global_load_lds_dwordx4 v0, s[0:1]
	s_mov_b32 m0, s36
	s_cmp_eq_u32 s7, 1
	global_load_lds_dwordx4 v132, s[0:1]
	s_cselect_b64 s[0:1], -1, 0
	s_cmp_lg_u32 s7, 1
	s_cbranch_scc1 .LBB0_1390
	s_barrier
.LBB0_1390:
	v_and_b32_e32 v3, 15, v2
	v_and_b32_e32 v12, 48, v2
	v_lshlrev_b32_e32 v3, 6, v3
	v_lshlrev_b32_e32 v2, 2, v2
	v_or_b32_e32 v13, v3, v12
	s_lshl_b32 s7, s7, 13
	v_and_b32_e32 v2, 32, v2
	v_mov_b32_e32 v131, v1
	v_bitop3_b32 v3, v3, v2, v12 bitop3:0x36
	v_bitop3_b32 v12, v13, s7, v2 bitop3:0xde
	s_lshl_b32 s7, s8, 12
	v_lshl_add_u64 v[4:5], s[26:27], 0, v[130:131]
	v_mov_b32_e32 v135, v1
	s_and_b32 s7, s7, 0x3000
	v_lshl_add_u64 v[6:7], s[26:27], 0, v[134:135]
	v_or_b32_e32 v136, s7, v3
	s_add_i32 m0, s19, 0x18000
	v_lshl_add_u64 v[2:3], v[4:5], 0, s[70:71]
	v_lshl_add_u64 v[8:9], s[24:25], 0, v[0:1]
	v_mov_b32_e32 v133, v1
	s_waitcnt vmcnt(2)
	s_barrier
	global_load_lds_dwordx4 v[2:3], off
	v_lshl_add_u64 v[2:3], v[6:7], 0, s[70:71]
	s_add_i32 m0, s19, 0x1a000
	s_add_i32 s37, s19, 0x8000
	s_add_i32 s38, s19, 0xa000
	v_lshl_add_u64 v[10:11], s[24:25], 0, v[132:133]
	global_load_lds_dwordx4 v[2:3], off
	v_lshl_add_u64 v[2:3], v[8:9], 0, s[70:71]
	s_mov_b32 m0, s37
	s_add_u32 s8, s26, 0x10080
	global_load_lds_dwordx4 v[2:3], off
	v_lshl_add_u64 v[2:3], v[10:11], 0, s[70:71]
	s_mov_b32 m0, s38
	s_addc_u32 s9, s27, 0
	global_load_lds_dwordx4 v[2:3], off
	s_add_i32 m0, s19, 0x1c000
	v_lshl_add_u64 v[2:3], s[8:9], 0, v[130:131]
	global_load_lds_dwordx4 v[2:3], off
	v_lshl_add_u64 v[2:3], s[8:9], 0, v[134:135]
	s_add_i32 m0, s19, 0x1e000
	s_cmpk_lt_u32 s6, 0x100
	global_load_lds_dwordx4 v[2:3], off
	s_waitcnt vmcnt(6)
	s_cselect_b64 s[8:9], -1, 0
	s_add_i32 s39, s100, s39
	v_add_u32_e32 v137, 0, v12
	s_mov_b64 s[16:17], s[26:27]
	s_mov_b64 s[14:15], s[24:25]
	s_barrier
	s_branch .LBB0_1393

.LBB0_1393:
	s_cmp_lt_i32 s39, s101
	v_mov_b32_e32 v254, v228
	s_cselect_b64 s[22:23], -1, 0
	s_cmp_ge_i32 s39, s101
	s_cbranch_scc1 .LBB0_1395
	s_cmpk_eq_i32 s101, 0x1f0
	s_cselect_b32 s13, 0x200, 0
	s_add_i32 s13, s13, s39
	s_cmpk_eq_i32 s101, 0x218
	s_cselect_b32 s11, 0x1f0, 0
	s_cmpk_ge_i32 s39, 0x200
	s_cselect_b32 s11, s11, 0
	s_add_i32 s13, s13, s11
	s_ashr_i32 s6, s13, 31
	s_lshr_b32 s6, s6, 30
	s_add_i32 s6, s13, s6
	s_ashr_i32 s10, s6, 2
	s_and_b32 s6, s6, -4
	s_ashr_i32 s11, s10, 31
	s_sub_i32 s12, s13, s6
	s_lshl_b64 s[6:7], s[10:11], 17
	s_add_u32 s14, s29, s6
	s_addc_u32 s15, s30, s7
	s_ashr_i32 s13, s12, 31
	s_lshl_b64 s[6:7], s[12:13], 17
	s_add_u32 s16, s21, s6
	s_addc_u32 s17, s31, s7

.LBB0_1401:
	s_cmpk_eq_i32 s101, 0x1f0
	s_cbranch_scc0 .Lp7_late_done
	s_movk_i32 s101, 0
	s_branch .Lp7_xbar
